# barrier after layer-0 P7 is a global sync again (without write-back): layer-1 weight conversion in P1 overwrites weights other XCDs may still read in P6/P7
# speedup vs baseline: 1.0028x; 1.0028x over previous
.LBB0_1388:
	s_lshl_b32 s6, s6, 6
	s_add_i32 s82, s6, 0x500
	s_lshl_b64 s[8:9], s[82:83], 2
	s_add_u32 s8, s42, s8
	s_addc_u32 s9, s43, s9
	v_mov_b64_e32 v[4:5], s[8:9]
	flat_atomic_add v3, v[4:5], v228 sc0
	v_cvt_f32_u32_e32 v1, v2
	v_sub_u32_e32 v4, 0, v2
	v_rcp_iflag_f32_e32 v1, v1
	s_nop 0
	v_mul_f32_e32 v1, 0x4f7ffffe, v1
	v_cvt_u32_f32_e32 v1, v1
	v_mul_lo_u32 v4, v4, v1
	v_mul_hi_u32 v4, v1, v4
	v_add_u32_e32 v1, v1, v4
	s_waitcnt vmcnt(0) lgkmcnt(0)
	v_mul_hi_u32 v1, v3, v1
	v_mul_lo_u32 v4, v1, v2
	v_sub_u32_e32 v4, v3, v4
	v_cmp_ge_u32_e32 vcc, v4, v2
	v_add_u32_e32 v5, 1, v1
	s_nop 0
	v_cndmask_b32_e32 v1, v1, v5, vcc
	v_sub_u32_e32 v5, v4, v2
	v_cndmask_b32_e32 v4, v4, v5, vcc
	v_cmp_ge_u32_e32 vcc, v4, v2
	v_add_u32_e32 v4, 1, v1
	s_nop 0
	v_cndmask_b32_e32 v1, v1, v4, vcc
	v_add_u32_e32 v4, 1, v3
	v_mad_u64_u32 v[2:3], s[8:9], v2, v1, v[2:3]
	v_cmp_ne_u32_e32 vcc, v4, v2
	s_and_saveexec_b64 s[8:9], vcc
	s_xor_b64 s[8:9], exec, s[8:9]
	s_cbranch_execz .LBB0_1401
	s_cmp_eq_u32 s100, 0
	s_cbranch_scc1 .Lnf_7
	s_cmp_lt_u32 s101, 7
	s_cbranch_scc1 .Lnf_7
	s_add_i32 s82, s6, 0x900
	s_lshl_b64 s[10:11], s[82:83], 2
	s_add_u32 s10, s42, s10
	s_addc_u32 s11, s43, s11
	v_mov_b64_e32 v[2:3], s[10:11]

.LBB0_1402:
	s_cmp_eq_u32 s100, 0
	s_cbranch_scc1 .Lfl_7
	s_cmp_lt_u32 s101, 7
	s_cbranch_scc1 .Lfl_7
	s_add_i32 s82, s6, 0x900
	s_lshl_b64 s[10:11], s[82:83], 2
	s_add_u32 s10, s42, s10
	s_addc_u32 s11, s43, s11
	v_mov_b64_e32 v[0:1], s[10:11]
	flat_atomic_add v[0:1], v228
	s_waitcnt vmcnt(0)
	s_branch .Ltramp_7
.Lfl_7:
	s_add_i32 s101, s101, 1
	v_mov_b32_e32 v1, s42
	v_add_co_u32_e32 v2, vcc, 0x3000, v1
	v_mov_b32_e32 v1, s43
	s_cmp_lg_u32 s100, 0
	s_cbranch_scc1 .Lnowb_7
	buffer_wbl2 sc1
.Lnowb_7:
	s_waitcnt vmcnt(0)
	v_addc_co_u32_e32 v3, vcc, 0, v1, vcc
	flat_atomic_add v1, v[2:3], v228 offset:1024 sc0
	v_cvt_f32_u32_e32 v2, v0
	v_sub_u32_e32 v3, 0, v0
	s_mov_b64 s[12:13], -1
	v_rcp_iflag_f32_e32 v2, v2
	s_nop 0
	v_mul_f32_e32 v2, 0x4f7ffffe, v2
	v_cvt_u32_f32_e32 v2, v2
	v_mul_lo_u32 v3, v3, v2
	v_mul_hi_u32 v3, v2, v3
	v_add_u32_e32 v2, v2, v3
	s_waitcnt vmcnt(0) lgkmcnt(0)
	v_mul_hi_u32 v2, v1, v2
	v_mul_lo_u32 v3, v2, v0
	v_sub_u32_e32 v3, v1, v3
	v_cmp_ge_u32_e32 vcc, v3, v0
	v_add_u32_e32 v4, 1, v2
	s_nop 0
	v_cndmask_b32_e32 v2, v2, v4, vcc
	v_sub_u32_e32 v4, v3, v0
	v_cndmask_b32_e32 v3, v3, v4, vcc
	v_cmp_ge_u32_e32 vcc, v3, v0
	v_add_u32_e32 v3, 1, v2
	s_nop 0
	v_cndmask_b32_e32 v2, v2, v3, vcc
	v_add_u32_e32 v3, 1, v1
	v_mad_u64_u32 v[0:1], s[8:9], v0, v2, v[0:1]
	s_add_u32 s8, s42, 0x3400
	s_addc_u32 s9, s43, 0
	v_cmp_ne_u32_e32 vcc, v3, v0
	v_mov_b32_e32 v3, v0
	v_mov_b64_e32 v[0:1], s[8:9]
	s_and_saveexec_b64 s[10:11], vcc
	s_cbranch_execz .LBB0_1414
	v_mov_b64_e32 v[0:1], s[8:9]
	flat_load_dword v0, v[0:1] sc1
	s_mov_b64 s[16:17], 0
	s_waitcnt vmcnt(0) lgkmcnt(0)
	v_cmp_lt_u32_e32 vcc, v0, v3
	s_and_saveexec_b64 s[14:15], vcc
	s_cbranch_execz .LBB0_1413
	s_add_u32 s12, s42, 0x200
	s_addc_u32 s13, s43, 0
	s_mov_b32 s7, 1
	s_branch .LBB0_1406
